# loop-edge edit (guide 7.12 step 2) in the DIFF loop: row-max tail v_max x3 + v_cmp moved above the last P.V MFMA so the uniform branch test resolves under it
# speedup vs baseline: 1.0059x; 1.0059x over previous
; __device__ __forceinline__ void finishSM(f32x16& p0, f32x16& p1, float alpha, float& l_reg, bf16x8& pa0, bf16x8& pa1, bf16x8& pa2, bf16x8& pa3) {
; #pragma unroll
;   for (int r = 0; r < 16; ++r) p1[r] = __builtin_amdgcn_exp2f(p1[r]);
;   float ps = 0;
; #pragma unroll
;   for (int r = 0; r < 16; ++r) ps += p0[r];
; #pragma unroll
;   for (int r = 0; r < 16; ++r) ps += p1[r];
;   { auto rr = __builtin_amdgcn_permlane32_swap(__float_as_uint(ps), __float_as_uint(ps), false, false);
;     ps = __uint_as_float(rr[0]) + __uint_as_float(rr[1]); }
;   l_reg = l_reg * alpha + ps;
;     ...
;   PK4(p0, 0, pa0); PK4(p0, 8, pa1); PK4(p1, 0, pa2); PK4(p1, 8, pa3);
;     ...
; }
; template <int DQK, int KW, int QSP> __device__ __forceinline__ void qkt(f32x16& p0, f32x16& p1, const char* Ks, const int (&kb)[4], const bf16x8* qr, const char* qsp, const f32x16& cinit) {
;   p0 = cinit; p1 = cinit;
;   constexpr int N = DQK / 16;
;     ...
;   bf16x8 f0[2], f1[2];
;   f0[0] = KRD(0, 1); f1[0] = KRD(0, 0);
; #pragma unroll
;   for (int d0 = 0; d0 < N; ++d0) {
;     if (d0 + 1 < N) { f0[(d0 + 1) & 1] = KRD(d0 + 1, 1); f1[(d0 + 1) & 1] = KRD(d0 + 1, 0); }
;     __builtin_amdgcn_sched_barrier(0x406);
;     bf16x8 qf;
;     if constexpr (QSP > 0) { if (d0 >= N - QSP) qf = *reinterpret_cast<const bf16x8*>(qsp + (d0 - (N - QSP)) * 1024); else qf = qr[d0]; } else qf = qr[d0];
;     p0 = __builtin_amdgcn_mfma_f32_32x32x16_bf16(f0[d0 & 1], qf, p0, 0, 0, 0);
;     p1 = __builtin_amdgcn_mfma_f32_32x32x16_bf16(f1[d0 & 1], qf, p1, 0, 0, 0);
;     __builtin_amdgcn_sched_barrier(0x406); }
.LBB0_316:
	s_lshl_b32 s10, s35, 14
	s_add_i32 s8, s10, 0
	v_add_u32_e32 v102, s8, v183
	ds_read_b128 v[98:101], v102 offset:49152
	v_add_u32_e32 v103, s8, v197
	ds_read_b128 v[200:203], v102 offset:57344
	ds_read_b128 v[222:225], v103 offset:49152
	ds_read_b128 v[226:229], v103 offset:57344
	v_add_u32_e32 v204, s8, v196
	v_exp_f32_e32 v205, v85
	v_exp_f32_e32 v97, v97
	s_waitcnt lgkmcnt(3)
	v_mfma_f32_32x32x16_bf16 v[114:129], v[98:101], v[142:145], v[66:81]
	s_waitcnt lgkmcnt(2)
	v_mfma_f32_32x32x16_bf16 v[98:113], v[200:203], v[142:145], v[66:81]
	ds_read_b128 v[200:203], v204 offset:49152
	ds_read_b128 v[230:233], v204 offset:57344
	v_add_u32_e32 v204, s8, v198
	s_waitcnt lgkmcnt(3)
	v_mfma_f32_32x32x16_bf16 v[114:129], v[222:225], v[138:141], v[114:129]
	s_waitcnt lgkmcnt(2)
	v_mfma_f32_32x32x16_bf16 v[98:113], v[226:229], v[138:141], v[98:113]
	ds_read_b128 v[222:225], v204 offset:49152
	ds_read_b128 v[226:229], v204 offset:57344
	v_exp_f32_e32 v204, v84
	s_waitcnt lgkmcnt(3)
	v_mfma_f32_32x32x16_bf16 v[114:129], v[200:203], v[134:137], v[114:129]
	v_exp_f32_e32 v202, v82
	v_add_f32_e32 v82, 0, v219
	v_add_f32_e32 v82, v221, v82
	v_add_f32_e32 v82, v217, v82
	v_add_f32_e32 v82, v220, v82
	v_add_f32_e32 v82, v215, v82
	v_add_f32_e32 v82, v218, v82
	v_add_f32_e32 v82, v214, v82
	v_add_f32_e32 v82, v216, v82
	v_add_f32_e32 v82, v211, v82
	v_add_f32_e32 v82, v213, v82
	v_add_f32_e32 v82, v209, v82
	v_add_f32_e32 v82, v212, v82
	s_waitcnt lgkmcnt(2)
	v_mfma_f32_32x32x16_bf16 v[98:113], v[230:233], v[134:137], v[98:113]
	v_add_f32_e32 v82, v207, v82
	v_exp_f32_e32 v203, v83
	v_add_f32_e32 v82, v210, v82
	v_add_f32_e32 v82, v206, v82
	v_add_f32_e32 v82, v208, v82
	v_add_f32_e32 v82, v202, v82
	v_add_f32_e32 v82, v203, v82
	s_waitcnt lgkmcnt(1)
	v_mfma_f32_32x32x16_bf16 v[114:129], v[222:225], v[130:133], v[114:129]
	v_exp_f32_e32 v222, v86
	v_exp_f32_e32 v223, v87
	v_exp_f32_e32 v224, v88
	v_add_f32_e32 v82, v204, v82
	v_exp_f32_e32 v225, v89
	v_add_f32_e32 v82, v205, v82
	v_add_f32_e32 v82, v222, v82
	s_waitcnt lgkmcnt(0)
	v_mfma_f32_32x32x16_bf16 v[98:113], v[226:229], v[130:133], v[98:113]
	v_exp_f32_e32 v226, v90
	v_exp_f32_e32 v227, v91
	v_add_f32_e32 v82, v223, v82
	v_exp_f32_e32 v228, v92
	v_add_f32_e32 v82, v224, v82
	v_exp_f32_e32 v229, v93
	v_add_f32_e32 v82, v225, v82
	v_exp_f32_e32 v230, v94
	v_add_f32_e32 v82, v226, v82
	v_exp_f32_e32 v231, v95
	v_add_f32_e32 v82, v227, v82
	v_exp_f32_e32 v232, v96
	v_add_f32_e32 v82, v228, v82
	v_add_f32_e32 v82, v229, v82
	v_add_f32_e32 v82, v230, v82
	v_add_f32_e32 v82, v231, v82
	v_add_f32_e32 v82, v232, v82
	v_add_f32_e32 v200, v97, v82
	v_mov_b32_e32 v201, v200
	v_cvt_pk_bf16_f32 v82, v219, v221
	v_cvt_pk_bf16_f32 v83, v217, v220
	v_cvt_pk_bf16_f32 v84, v215, v218
	s_nop 1
	v_permlane32_swap_b32_e32 v200, v201
	v_cvt_pk_bf16_f32 v85, v214, v216
	v_permlane32_swap_b32_e32 v82, v84
	v_cvt_pk_bf16_f32 v86, v211, v213
	v_cvt_pk_bf16_f32 v87, v209, v212
	v_cvt_pk_bf16_f32 v88, v207, v210
	v_cvt_pk_bf16_f32 v89, v206, v208
	v_cvt_pk_bf16_f32 v90, v202, v203
	v_cvt_pk_bf16_f32 v91, v204, v205
	v_cvt_pk_bf16_f32 v92, v222, v223
	v_cvt_pk_bf16_f32 v93, v224, v225
	v_cvt_pk_bf16_f32 v94, v226, v227
	v_cvt_pk_bf16_f32 v95, v228, v229
	v_cvt_pk_bf16_f32 v96, v230, v231
	v_cvt_pk_bf16_f32 v97, v232, v97
	v_permlane32_swap_b32_e32 v83, v85
	v_permlane32_swap_b32_e32 v86, v88
	v_permlane32_swap_b32_e32 v87, v89
	v_permlane32_swap_b32_e32 v90, v92
	v_permlane32_swap_b32_e32 v91, v93
	v_permlane32_swap_b32_e32 v94, v96
	v_permlane32_swap_b32_e32 v95, v97
	s_lshl_b32 s13, s12, 14
	s_add_i32 s11, s13, 0
	v_add_u32_e32 v202, s11, v192
	s_waitcnt vmcnt(0)
	s_waitcnt vmcnt(3)
	ds_write_b128 v202, v[146:149]
	v_add_u32_e32 v146, s11, v193
	s_waitcnt vmcnt(1)
	ds_write_b128 v146, v[150:153]
	v_add_u32_e32 v146, s11, v194
	s_mov_b32 s8, 0xfffa0000
	s_waitcnt vmcnt(1)
	ds_write_b128 v146, v[154:157] offset:49152
	s_waitcnt vmcnt(0)
; #define SBAR() __builtin_amdgcn_sched_barrier(0)
; template <bool FIRST> __device__ __forceinline__ void partialSM_ps(f32x16& p0, f32x16& p1, float& m_reg, float& alpha, f32x16& negm) {
;   float pmax = p0[0];
; #pragma unroll
;   for (int r = 1; r < 16; ++r) pmax = fmaxf(pmax, p0[r]);
; #pragma unroll
;   for (int r = 0; r < 16; ++r) pmax = fmaxf(pmax, p1[r]);
;   { auto rr = __builtin_amdgcn_permlane32_swap(__float_as_uint(pmax), __float_as_uint(pmax), false, false);
;     pmax = fmaxf(__uint_as_float(rr[0]), __uint_as_float(rr[1])); }
;   alpha = 1.f;
;   if (FIRST || !__builtin_expect(__all(pmax <= THRL), 1)) {
; template <int D0> __device__ __forceinline__ void pv_one(f32x16& od, int vb, bf16x8 pa0, bf16x8 pa1, bf16x8 pa2, bf16x8 pa3) {
;   const s16x4 l0 = tr_read<v_rd_off(D0, 0, 0)>(vb), h0 = tr_read<v_rd_off(D0, 0, 1)>(vb), l1 = tr_read<v_rd_off(D0, 1, 0)>(vb), h1 = tr_read<v_rd_off(D0, 1, 1)>(vb);
;   const s16x4 l2 = tr_read<v_rd_off(D0, 2, 0)>(vb), h2 = tr_read<v_rd_off(D0, 2, 1)>(vb), l3 = tr_read<v_rd_off(D0, 3, 0)>(vb), h3 = tr_read<v_rd_off(D0, 3, 1)>(vb);
;   asm volatile("s_waitcnt lgkmcnt(0)" ::: "memory"); SBAR();
;     ...
;   od = __builtin_amdgcn_mfma_f32_32x32x16_bf16(pa0, PK(l0, h0), od, 0, 0, 0);
;   od = __builtin_amdgcn_mfma_f32_32x32x16_bf16(pa1, PK(l1, h1), od, 0, 0, 0);
;   od = __builtin_amdgcn_mfma_f32_32x32x16_bf16(pa2, PK(l2, h2), od, 0, 0, 0);
;   od = __builtin_amdgcn_mfma_f32_32x32x16_bf16(pa3, PK(l3, h3), od, 0, 0, 0);
;     ...
; }
	ds_write_b128 v146, v[158:161] offset:57344
	v_add_co_u32_e32 v146, vcc, s8, v166
	s_mov_b32 s8, 0xfffc0000
	s_nop 0
	v_addc_co_u32_e32 v147, vcc, -1, v167, vcc
	v_add_co_u32_e32 v150, vcc, s8, v166
	s_mov_b32 s8, 0xfb7a0000
	s_nop 0
	v_addc_co_u32_e32 v151, vcc, -1, v167, vcc
	v_add_co_u32_e32 v154, vcc, s8, v166
	s_mov_b32 s8, 0xfb7c0000
	s_nop 0
	v_addc_co_u32_e32 v155, vcc, -1, v167, vcc
	v_add_co_u32_e32 v158, vcc, s8, v166
	global_load_dwordx4 v[146:149], v[146:147], off
	s_nop 0
	global_load_dwordx4 v[150:153], v[150:151], off
	v_addc_co_u32_e32 v159, vcc, -1, v167, vcc
	global_load_dwordx4 v[154:157], v[154:155], off
	s_nop 0
	global_load_dwordx4 v[158:161], v[158:159], off
	v_lshl_add_u32 v218, s9, 14, v181
	ds_read_b64_tr_b16 v[202:203], v218 offset:0
	ds_read_b64_tr_b16 v[204:205], v218 offset:0x800
	ds_read_b64_tr_b16 v[206:207], v218 offset:0x1000
	ds_read_b64_tr_b16 v[208:209], v218 offset:0x1800
	ds_read_b64_tr_b16 v[210:211], v218 offset:0x2000
	ds_read_b64_tr_b16 v[212:213], v218 offset:0x2800
	ds_read_b64_tr_b16 v[214:215], v218 offset:0x3000
	ds_read_b64_tr_b16 v[216:217], v218 offset:0x3800
	s_waitcnt lgkmcnt(6)
	s_nop 0
	v_mfma_f32_32x32x16_bf16 v[2:17], v[82:85], v[202:205], v[2:17]
	ds_read_b64_tr_b16 v[202:203], v218 offset:0x200
	ds_read_b64_tr_b16 v[204:205], v218 offset:0xa00
	s_waitcnt lgkmcnt(6)
	v_mfma_f32_32x32x16_bf16 v[2:17], v[86:89], v[206:209], v[2:17]
	ds_read_b64_tr_b16 v[206:207], v218 offset:0x1200
	ds_read_b64_tr_b16 v[208:209], v218 offset:0x1a00
	s_waitcnt lgkmcnt(6)
	v_mfma_f32_32x32x16_bf16 v[2:17], v[90:93], v[210:213], v[2:17]
	ds_read_b64_tr_b16 v[210:211], v218 offset:0x2200
	ds_read_b64_tr_b16 v[212:213], v218 offset:0x2a00
	s_waitcnt lgkmcnt(6)
	v_mfma_f32_32x32x16_bf16 v[2:17], v[94:97], v[214:217], v[2:17]
	ds_read_b64_tr_b16 v[214:215], v218 offset:0x3200
	ds_read_b64_tr_b16 v[216:217], v218 offset:0x3a00
	s_waitcnt lgkmcnt(6)
	v_mfma_f32_32x32x16_bf16 v[50:65], v[82:85], v[202:205], v[50:65]
	ds_read_b64_tr_b16 v[202:203], v218 offset:0x400
	ds_read_b64_tr_b16 v[204:205], v218 offset:0xc00
	s_waitcnt lgkmcnt(6)
	v_mfma_f32_32x32x16_bf16 v[50:65], v[86:89], v[206:209], v[50:65]
	ds_read_b64_tr_b16 v[206:207], v218 offset:0x1400
	ds_read_b64_tr_b16 v[208:209], v218 offset:0x1c00
	s_waitcnt lgkmcnt(6)
	v_mfma_f32_32x32x16_bf16 v[50:65], v[90:93], v[210:213], v[50:65]
	ds_read_b64_tr_b16 v[210:211], v218 offset:0x2400
	ds_read_b64_tr_b16 v[212:213], v218 offset:0x2c00
	s_waitcnt lgkmcnt(6)
	v_mfma_f32_32x32x16_bf16 v[50:65], v[94:97], v[214:217], v[50:65]
	ds_read_b64_tr_b16 v[214:215], v218 offset:0x3400
	ds_read_b64_tr_b16 v[216:217], v218 offset:0x3c00
	s_waitcnt lgkmcnt(6)
	v_mfma_f32_32x32x16_bf16 v[34:49], v[82:85], v[202:205], v[34:49]
	ds_read_b64_tr_b16 v[202:203], v218 offset:0x600
	ds_read_b64_tr_b16 v[204:205], v218 offset:0xe00
	s_waitcnt lgkmcnt(6)
	v_mfma_f32_32x32x16_bf16 v[34:49], v[86:89], v[206:209], v[34:49]
	ds_read_b64_tr_b16 v[206:207], v218 offset:0x1600
	ds_read_b64_tr_b16 v[208:209], v218 offset:0x1e00
	s_waitcnt lgkmcnt(6)
	v_mfma_f32_32x32x16_bf16 v[34:49], v[90:93], v[210:213], v[34:49]
	ds_read_b64_tr_b16 v[210:211], v218 offset:0x2600
	ds_read_b64_tr_b16 v[212:213], v218 offset:0x2e00
	s_waitcnt lgkmcnt(6)
	v_mfma_f32_32x32x16_bf16 v[34:49], v[94:97], v[214:217], v[34:49]
	ds_read_b64_tr_b16 v[214:215], v218 offset:0x3600
	ds_read_b64_tr_b16 v[216:217], v218 offset:0x3e00
	s_waitcnt lgkmcnt(6)
	v_mfma_f32_32x32x16_bf16 v[18:33], v[82:85], v[202:205], v[18:33]
	v_max_f32_e32 v82, v115, v115
	v_max_f32_e32 v83, v114, v114
	v_max_f32_e32 v82, v83, v82
	v_max3_f32 v82, v82, v116, v117
	v_max3_f32 v82, v82, v118, v119
	v_max3_f32 v82, v82, v120, v121
	v_max3_f32 v82, v82, v122, v123
	s_waitcnt lgkmcnt(4)
	v_mfma_f32_32x32x16_bf16 v[18:33], v[86:89], v[206:209], v[18:33]
	v_max3_f32 v82, v82, v124, v125
	v_max3_f32 v82, v82, v126, v127
	v_max3_f32 v82, v82, v128, v129
	v_max3_f32 v82, v82, v98, v99
	v_max3_f32 v82, v82, v100, v101
	v_max3_f32 v82, v82, v102, v103
	v_max3_f32 v82, v82, v104, v105
	s_waitcnt lgkmcnt(2)
	v_mfma_f32_32x32x16_bf16 v[18:33], v[90:93], v[210:213], v[18:33]
	v_max3_f32 v82, v82, v106, v107
	v_max3_f32 v82, v82, v108, v109
	v_max3_f32 v82, v82, v110, v111
	v_max3_f32 v82, v82, v112, v113
	v_mov_b32_e32 v83, v82
	s_nop 1
	v_permlane32_swap_b32_e32 v82, v83
	s_nop 0
	v_max_f32_e32 v83, v83, v83
	v_max_f32_e32 v82, v82, v82
	v_max_f32_e32 v82, v82, v83
	v_cmp_ge_f32_e32 vcc, s0, v82
	s_waitcnt lgkmcnt(0)
	v_mfma_f32_32x32x16_bf16 v[18:33], v[94:97], v[214:217], v[18:33]
	s_cmp_eq_u64 vcc, exec
	s_cbranch_scc0 .LBB0_331
	v_mov_b32_e32 v203, 1.0

; #define SBAR() __builtin_amdgcn_sched_barrier(0)
; template <bool FIRST> __device__ __forceinline__ void partialSM_ps(f32x16& p0, f32x16& p1, float& m_reg, float& alpha, f32x16& negm) {
;   float pmax = p0[0];
; #pragma unroll
;   for (int r = 1; r < 16; ++r) pmax = fmaxf(pmax, p0[r]);
; #pragma unroll
;   for (int r = 0; r < 16; ++r) pmax = fmaxf(pmax, p1[r]);
;   { auto rr = __builtin_amdgcn_permlane32_swap(__float_as_uint(pmax), __float_as_uint(pmax), false, false);
;     pmax = fmaxf(__uint_as_float(rr[0]), __uint_as_float(rr[1])); }
;   alpha = 1.f;
;   if (FIRST || !__builtin_expect(__all(pmax <= THRL), 1)) {
; template <int D0> __device__ __forceinline__ void pv_one(f32x16& od, int vb, bf16x8 pa0, bf16x8 pa1, bf16x8 pa2, bf16x8 pa3) {
;   const s16x4 l0 = tr_read<v_rd_off(D0, 0, 0)>(vb), h0 = tr_read<v_rd_off(D0, 0, 1)>(vb), l1 = tr_read<v_rd_off(D0, 1, 0)>(vb), h1 = tr_read<v_rd_off(D0, 1, 1)>(vb);
;   const s16x4 l2 = tr_read<v_rd_off(D0, 2, 0)>(vb), h2 = tr_read<v_rd_off(D0, 2, 1)>(vb), l3 = tr_read<v_rd_off(D0, 3, 0)>(vb), h3 = tr_read<v_rd_off(D0, 3, 1)>(vb);
;   asm volatile("s_waitcnt lgkmcnt(0)" ::: "memory"); SBAR();
;     ...
;   od = __builtin_amdgcn_mfma_f32_32x32x16_bf16(pa0, PK(l0, h0), od, 0, 0, 0);
;   od = __builtin_amdgcn_mfma_f32_32x32x16_bf16(pa1, PK(l1, h1), od, 0, 0, 0);
;   od = __builtin_amdgcn_mfma_f32_32x32x16_bf16(pa2, PK(l2, h2), od, 0, 0, 0);
;   od = __builtin_amdgcn_mfma_f32_32x32x16_bf16(pa3, PK(l3, h3), od, 0, 0, 0);
;     ...
; }
.LBB0_324:
	v_add_u32_e32 v202, s10, v181
	ds_read_b64_tr_b16 v[206:207], v202 offset:0
	ds_read_b64_tr_b16 v[208:209], v202 offset:0x800
	ds_read_b64_tr_b16 v[210:211], v202 offset:0x1000
	ds_read_b64_tr_b16 v[212:213], v202 offset:0x1800
	ds_read_b64_tr_b16 v[214:215], v202 offset:0x2000
	ds_read_b64_tr_b16 v[216:217], v202 offset:0x2800
	ds_read_b64_tr_b16 v[218:219], v202 offset:0x3000
	ds_read_b64_tr_b16 v[220:221], v202 offset:0x3800
	s_waitcnt lgkmcnt(6)
	s_nop 0
	v_mfma_f32_32x32x16_bf16 v[2:17], v[98:101], v[206:209], v[2:17]
	ds_read_b64_tr_b16 v[206:207], v202 offset:0x200
	ds_read_b64_tr_b16 v[208:209], v202 offset:0xa00
	s_waitcnt lgkmcnt(6)
	v_mfma_f32_32x32x16_bf16 v[2:17], v[102:105], v[210:213], v[2:17]
	ds_read_b64_tr_b16 v[210:211], v202 offset:0x1200
	ds_read_b64_tr_b16 v[212:213], v202 offset:0x1a00
	s_waitcnt lgkmcnt(6)
	v_mfma_f32_32x32x16_bf16 v[2:17], v[106:109], v[214:217], v[2:17]
	ds_read_b64_tr_b16 v[214:215], v202 offset:0x2200
	ds_read_b64_tr_b16 v[216:217], v202 offset:0x2a00
	s_waitcnt lgkmcnt(6)
	v_mfma_f32_32x32x16_bf16 v[2:17], v[110:113], v[218:221], v[2:17]
	ds_read_b64_tr_b16 v[218:219], v202 offset:0x3200
	ds_read_b64_tr_b16 v[220:221], v202 offset:0x3a00
	s_waitcnt lgkmcnt(6)
	v_mfma_f32_32x32x16_bf16 v[50:65], v[98:101], v[206:209], v[50:65]
	ds_read_b64_tr_b16 v[206:207], v202 offset:0x400
	ds_read_b64_tr_b16 v[208:209], v202 offset:0xc00
	s_waitcnt lgkmcnt(6)
	v_mfma_f32_32x32x16_bf16 v[50:65], v[102:105], v[210:213], v[50:65]
	ds_read_b64_tr_b16 v[210:211], v202 offset:0x1400
	ds_read_b64_tr_b16 v[212:213], v202 offset:0x1c00
	s_waitcnt lgkmcnt(6)
	v_mfma_f32_32x32x16_bf16 v[50:65], v[106:109], v[214:217], v[50:65]
	ds_read_b64_tr_b16 v[214:215], v202 offset:0x2400
	ds_read_b64_tr_b16 v[216:217], v202 offset:0x2c00
	s_waitcnt lgkmcnt(6)
	v_mfma_f32_32x32x16_bf16 v[50:65], v[110:113], v[218:221], v[50:65]
	ds_read_b64_tr_b16 v[218:219], v202 offset:0x3400
	ds_read_b64_tr_b16 v[220:221], v202 offset:0x3c00
	s_waitcnt lgkmcnt(6)
	v_mfma_f32_32x32x16_bf16 v[34:49], v[98:101], v[206:209], v[34:49]
	ds_read_b64_tr_b16 v[206:207], v202 offset:0x600
	ds_read_b64_tr_b16 v[208:209], v202 offset:0xe00
	s_waitcnt lgkmcnt(6)
	v_mfma_f32_32x32x16_bf16 v[34:49], v[102:105], v[210:213], v[34:49]
	ds_read_b64_tr_b16 v[210:211], v202 offset:0x1600
	ds_read_b64_tr_b16 v[212:213], v202 offset:0x1e00
	s_waitcnt lgkmcnt(6)
	v_mfma_f32_32x32x16_bf16 v[34:49], v[106:109], v[214:217], v[34:49]
	ds_read_b64_tr_b16 v[214:215], v202 offset:0x2600
	ds_read_b64_tr_b16 v[216:217], v202 offset:0x2e00
	s_waitcnt lgkmcnt(6)
	v_mfma_f32_32x32x16_bf16 v[34:49], v[110:113], v[218:221], v[34:49]
	ds_read_b64_tr_b16 v[218:219], v202 offset:0x3600
	ds_read_b64_tr_b16 v[220:221], v202 offset:0x3e00
	s_waitcnt lgkmcnt(6)
	v_mfma_f32_32x32x16_bf16 v[18:33], v[98:101], v[206:209], v[18:33]
	v_max_f32_e32 v98, v115, v115
	v_max_f32_e32 v99, v114, v114
	v_max_f32_e32 v98, v99, v98
	v_max3_f32 v98, v98, v116, v117
	v_max3_f32 v98, v98, v118, v119
	v_max3_f32 v98, v98, v120, v121
	v_max3_f32 v98, v98, v122, v123
	s_waitcnt lgkmcnt(4)
	v_mfma_f32_32x32x16_bf16 v[18:33], v[102:105], v[210:213], v[18:33]
	v_max3_f32 v98, v98, v124, v125
	v_max3_f32 v98, v98, v126, v127
	v_max3_f32 v98, v98, v128, v129
	v_max3_f32 v98, v98, v82, v83
	v_max3_f32 v98, v98, v84, v85
	v_max3_f32 v98, v98, v86, v87
	v_max3_f32 v98, v98, v88, v89
	s_waitcnt lgkmcnt(2)
	v_mfma_f32_32x32x16_bf16 v[18:33], v[106:109], v[214:217], v[18:33]
	v_max3_f32 v98, v98, v90, v91
	v_max3_f32 v98, v98, v92, v93
	v_max3_f32 v98, v98, v94, v95
	v_max3_f32 v98, v98, v96, v97
	v_mov_b32_e32 v99, v98
	s_nop 1
	v_permlane32_swap_b32_e32 v98, v99
	s_nop 0
	v_max_f32_e32 v99, v99, v99
	v_max_f32_e32 v98, v98, v98
	v_max_f32_e32 v98, v98, v99
	v_cmp_ge_f32_e32 vcc, s0, v98
	s_waitcnt lgkmcnt(0)
	v_mfma_f32_32x32x16_bf16 v[18:33], v[110:113], v[218:221], v[18:33]
	s_cmp_eq_u64 vcc, exec
	v_mov_b32_e32 v202, 1.0
	s_cbranch_scc0 .LBB0_332
